# attention queues: the 64 longest heavy diff items each followed by two light items (light q-blocks ascending), the remaining heavy items after them
# baseline (speedup 1.0000x reference)
.LBB0_840:
	s_andn2_b64 vcc, exec, s[38:39]
	s_cbranch_vccnz .LBB0_842
	s_add_i32 s4, s54, -12
	s_mul_i32 s30, s4, 0xab
	s_lshr_b32 s30, s30, 9
	s_mul_i32 s31, s30, 3
	s_sub_i32 s31, s4, s31
	s_andn2_b32 s50, 0x7f, s30
	s_lshl_b32 s30, s30, 1
	s_add_i32 s30, s30, s31
	s_add_i32 s30, s30, -1
	s_cmp_eq_u32 s31, 0
	s_cselect_b32 s50, s50, s30
	s_cselect_b32 s31, 1, 0
	s_sub_i32 s30, 0xff, s4
	s_cmpk_lt_u32 s4, 0xc0
	s_cselect_b32 s31, s31, 1
	s_cselect_b32 s50, s50, s30
	s_cmp_eq_u32 s31, 1
	v_readlane_b32 s4, v250, 18
	v_readlane_b32 s5, v250, 19
	s_cselect_b32 s6, 2, 1
	s_cselect_b32 s30, 3, 0
	s_and_b64 s[4:5], s[4:5], exec
	s_cselect_b32 s6, s30, s6
	s_mov_b64 s[4:5], 0
	s_mov_b32 s55, s71
